# lambda / bound parameter vectors touched before the pooling body so the two short serial loops ahead of attention hit the cache
# baseline (speedup 1.0000x reference)
; __device__ __forceinline__ int lane_id() { int l; asm volatile("v_mbcnt_lo_u32_b32 %0, -1, 0\n\tv_mbcnt_hi_u32_b32 %0, -1, %0" : "=v"(l)); return l; }
; __device__ __forceinline__ void pool_phase(const bf16_t* zp, bf16_t* mixed, const int wave_s) {
;     const int lane = lane_id(), c0 = lane * 8, half = 1 << (lane >> 4);
;     for (int r = blockIdx.x * 8 + wave_s; r < MTOK / 64; r += gridDim.x * 8) {
;         const int tok_base = r * 64, S = tok_base < NPROMPT ? SEQP : SEQS, pos0 = tok_base & (S - 1);
;         const bf16_t* zs = zp + (size_t)(tok_base - pos0) * 512 + c0;
;         bf16_t* ms = mixed + (size_t)(tok_base - pos0) * DM + 512 + c0;
; __global__ void __launch_bounds__(512) fwd_megakernel(Params p) {
;     ...
;         float d1 = 0.f, d2 = 0.f;
;         for (int i = 0; i < 64; ++i) { d1 += p.in[I_LQ1][i] * p.in[I_LK1][i]; d2 += p.in[I_LQ2][i] * p.in[I_LK2][i]; }
;         const float lam = __builtin_bit_cast(float, __builtin_amdgcn_readfirstlane(__builtin_bit_cast(int, __expf(d1) - __expf(d2) + 0.2f)));
;         float gq = 0.f, gk = 0.f;
;         for (int i = 0; i < 64; ++i) { gq = fmaxf(gq, fabsf(p.in[I_QG][i])); gk = fmaxf(gk, fabsf(p.in[I_KG][i])); }
.LBB0_309:
	s_or_b64 exec, exec, s[0:1]
	s_lshr_b32 s0, s33, 6
	s_add_i32 s23, s0, s23
	s_cmpk_lt_i32 s23, 0x800
	s_waitcnt lgkmcnt(0)
	s_barrier
	v_mbcnt_lo_u32_b32 v0, -1, 0
	v_mbcnt_hi_u32_b32 v0, -1, v0
	s_cbranch_scc0 .LBB0_362
	v_ashrrev_i32_e32 v4, 4, v0
	v_lshlrev_b32_e32 v0, 3, v0
	v_ashrrev_i32_e32 v1, 31, v0
	v_lshlrev_b64 v[0:1], 1, v[0:1]
	v_lshlrev_b32_e64 v26, v4, 1
	v_lshl_add_u64 v[2:3], s[80:81], 0, v[0:1]
	s_mov_b64 s[0:1], 0x19a00000
	v_lshl_add_u64 v[2:3], v[2:3], 0, s[0:1]
	v_cmp_lt_i32_e64 s[0:1], 7, v26
	v_cmp_lt_i32_e64 s[4:5], 6, v26
	v_cmp_lt_i32_e64 s[6:7], 5, v26
	v_cmp_lt_i32_e64 s[8:9], 4, v26
	v_cmp_lt_i32_e64 s[10:11], 3, v26
	v_cmp_lt_i32_e64 s[12:13], 2, v26
	v_cmp_lt_i32_e64 s[14:15], 1, v26
	v_cmp_ne_u32_e64 s[16:17], 31, v4
	s_lshl_b32 s33, s82, 3
	s_add_i32 s24, s70, s90
	s_mov_b32 s27, 0
	v_sub_u32_e32 v27, 0, v26
	s_movk_i32 s34, 0x1000
	v_mov_b32_e32 v5, 0
	s_mov_b32 s35, 0x19a00000
	global_load_dword v16, v5, s[48:49]
	global_load_dword v16, v5, s[48:49] offset:128
	global_load_dword v16, v5, s[50:51]
	global_load_dword v16, v5, s[50:51] offset:128
	global_load_dword v16, v5, s[56:57]
	global_load_dword v16, v5, s[56:57] offset:128
	global_load_dword v16, v5, s[58:59]
	global_load_dword v16, v5, s[58:59] offset:128
	global_load_dword v16, v5, s[44:45]
	global_load_dword v16, v5, s[44:45] offset:128
	global_load_dword v16, v5, s[46:47]
	global_load_dword v16, v5, s[46:47] offset:128
	s_branch .LBB0_312
